# v65 + wide in-projection k-loop: 9 MFMAs after the barrier (was 15; 12 in the previous version)
# baseline (speedup 1.0000x reference)
.LBB0_124:
	s_waitcnt lgkmcnt(0)
	s_mov_b32 s99, 0x10000
	s_mov_b32 s100, 0x80
	s_mov_b32 s101, 0
	s_add_i32 m0, s4, 0x10000
	s_nop 0
	global_load_lds_dwordx4 v[130:131], off
	v_lshl_add_u64 v[130:131], v[130:131], 0, s[100:101]
	s_add_i32 m0, s4, 0x18000
	s_nop 0
	global_load_lds_dwordx4 v[138:139], off
	v_lshl_add_u64 v[138:139], v[138:139], 0, s[100:101]
	s_add_i32 m0, s5, 0x10000
	s_nop 0
	global_load_lds_dwordx4 v[132:133], off
	v_lshl_add_u64 v[132:133], v[132:133], 0, s[100:101]
	s_add_i32 m0, s5, 0x18000
	s_nop 0
	global_load_lds_dwordx4 v[140:141], off
	v_lshl_add_u64 v[140:141], v[140:141], 0, s[100:101]
	s_add_i32 m0, s6, 0x10000
	s_nop 0
	global_load_lds_dwordx4 v[134:135], off
	v_lshl_add_u64 v[134:135], v[134:135], 0, s[100:101]
	s_add_i32 m0, s6, 0x18000
	s_nop 0
	global_load_lds_dwordx4 v[142:143], off
	v_lshl_add_u64 v[142:143], v[142:143], 0, s[100:101]
	s_add_i32 m0, s7, 0x10000
	s_nop 0
	global_load_lds_dwordx4 v[136:137], off
	v_lshl_add_u64 v[136:137], v[136:137], 0, s[100:101]
	s_add_i32 m0, s7, 0x18000
	s_nop 0
	global_load_lds_dwordx4 v[144:145], off
	v_lshl_add_u64 v[144:145], v[144:145], 0, s[100:101]
	v_add_u32_e32 v162, v149, v147
	v_add_u32_e32 v128, v149, v146
	ds_read_b128 v[150:153], v162 offset:32768
	ds_read_b128 v[154:157], v162 offset:34816
	ds_read_b128 v[158:161], v162 offset:36864
	ds_read_b128 v[162:165], v162 offset:38912
	ds_read_b128 v[166:169], v128 offset:0
	ds_read_b128 v[170:173], v128 offset:2048
	ds_read_b128 v[174:177], v128 offset:4096
	ds_read_b128 v[180:183], v128 offset:6144
	ds_read_b128 v[186:189], v128 offset:8192
	ds_read_b128 v[190:193], v128 offset:10240
	ds_read_b128 v[194:197], v128 offset:12288
	ds_read_b128 v[198:201], v128 offset:14336
	s_waitcnt lgkmcnt(4)
	v_mfma_f32_16x16x32_bf16 v[124:127], v[166:169], v[150:153], 0
	v_mfma_f32_16x16x32_bf16 v[120:123], v[166:169], v[154:157], 0
	v_mfma_f32_16x16x32_bf16 v[116:119], v[166:169], v[158:161], 0
	v_mfma_f32_16x16x32_bf16 v[112:115], v[166:169], v[162:165], 0
	v_mfma_f32_16x16x32_bf16 v[108:111], v[170:173], v[150:153], 0
	v_mfma_f32_16x16x32_bf16 v[104:107], v[170:173], v[154:157], 0
	v_mfma_f32_16x16x32_bf16 v[100:103], v[170:173], v[158:161], 0
	v_mfma_f32_16x16x32_bf16 v[96:99], v[170:173], v[162:165], 0
	v_mfma_f32_16x16x32_bf16 v[92:95], v[174:177], v[150:153], 0
	v_mfma_f32_16x16x32_bf16 v[84:87], v[174:177], v[154:157], 0
	v_mfma_f32_16x16x32_bf16 v[80:83], v[174:177], v[158:161], 0
	v_mfma_f32_16x16x32_bf16 v[76:79], v[174:177], v[162:165], 0
	v_mfma_f32_16x16x32_bf16 v[72:75], v[180:183], v[150:153], 0
	v_mfma_f32_16x16x32_bf16 v[68:71], v[180:183], v[154:157], 0
	v_mfma_f32_16x16x32_bf16 v[64:67], v[180:183], v[158:161], 0
	v_mfma_f32_16x16x32_bf16 v[60:63], v[180:183], v[162:165], 0
	v_add_u32_e32 v180, v148, v147
	v_add_u32_e32 v128, v148, v146
	ds_read_b128 v[166:169], v180 offset:32768
	ds_read_b128 v[170:173], v180 offset:34816
	ds_read_b128 v[174:177], v180 offset:36864
	ds_read_b128 v[180:183], v180 offset:38912
	ds_read_b128 v[202:205], v128 offset:0
	ds_read_b128 v[206:209], v128 offset:2048
	ds_read_b128 v[210:213], v128 offset:4096
	ds_read_b128 v[214:217], v128 offset:6144
	s_waitcnt lgkmcnt(8)
	v_mfma_f32_16x16x32_bf16 v[56:59], v[186:189], v[150:153], 0
	v_mfma_f32_16x16x32_bf16 v[52:55], v[186:189], v[154:157], 0
	v_mfma_f32_16x16x32_bf16 v[48:51], v[186:189], v[158:161], 0
	v_mfma_f32_16x16x32_bf16 v[44:47], v[186:189], v[162:165], 0
	v_mfma_f32_16x16x32_bf16 v[40:43], v[190:193], v[150:153], 0
	v_mfma_f32_16x16x32_bf16 v[36:39], v[190:193], v[154:157], 0
	v_mfma_f32_16x16x32_bf16 v[32:35], v[190:193], v[158:161], 0
	v_mfma_f32_16x16x32_bf16 v[28:31], v[190:193], v[162:165], 0
	v_mfma_f32_16x16x32_bf16 v[24:27], v[194:197], v[150:153], 0
	v_mfma_f32_16x16x32_bf16 v[20:23], v[194:197], v[154:157], 0
	v_mfma_f32_16x16x32_bf16 v[16:19], v[194:197], v[158:161], 0
	v_mfma_f32_16x16x32_bf16 v[12:15], v[194:197], v[162:165], 0
	v_mfma_f32_16x16x32_bf16 v[8:11], v[198:201], v[150:153], 0
	v_mfma_f32_16x16x32_bf16 v[4:7], v[198:201], v[154:157], 0
	v_mfma_f32_16x16x32_bf16 v[0:3], v[198:201], v[158:161], 0
	v_mfma_f32_16x16x32_bf16 v[88:91], v[198:201], v[162:165], 0
	ds_read_b128 v[150:153], v128 offset:8192
	ds_read_b128 v[154:157], v128 offset:10240
	ds_read_b128 v[158:161], v128 offset:12288
	ds_read_b128 v[162:165], v128 offset:14336
	s_waitcnt lgkmcnt(4)
	v_mfma_f32_16x16x32_bf16 v[124:127], v[202:205], v[166:169], v[124:127]
	v_mfma_f32_16x16x32_bf16 v[120:123], v[202:205], v[170:173], v[120:123]
	v_mfma_f32_16x16x32_bf16 v[116:119], v[202:205], v[174:177], v[116:119]
	v_mfma_f32_16x16x32_bf16 v[112:115], v[202:205], v[180:183], v[112:115]
	v_mfma_f32_16x16x32_bf16 v[108:111], v[206:209], v[166:169], v[108:111]
	v_mfma_f32_16x16x32_bf16 v[104:107], v[206:209], v[170:173], v[104:107]
	v_mfma_f32_16x16x32_bf16 v[100:103], v[206:209], v[174:177], v[100:103]
	v_mfma_f32_16x16x32_bf16 v[96:99], v[206:209], v[180:183], v[96:99]
	v_mfma_f32_16x16x32_bf16 v[92:95], v[210:213], v[166:169], v[92:95]
	v_mfma_f32_16x16x32_bf16 v[84:87], v[210:213], v[170:173], v[84:87]
	v_mfma_f32_16x16x32_bf16 v[80:83], v[210:213], v[174:177], v[80:83]
	v_mfma_f32_16x16x32_bf16 v[76:79], v[210:213], v[180:183], v[76:79]
	v_mfma_f32_16x16x32_bf16 v[72:75], v[214:217], v[166:169], v[72:75]
	v_mfma_f32_16x16x32_bf16 v[68:71], v[214:217], v[170:173], v[68:71]
	v_mfma_f32_16x16x32_bf16 v[64:67], v[214:217], v[174:177], v[64:67]
	v_mfma_f32_16x16x32_bf16 v[60:63], v[214:217], v[180:183], v[60:63]
	s_waitcnt lgkmcnt(0)
	v_mfma_f32_16x16x32_bf16 v[56:59], v[150:153], v[166:169], v[56:59]
	v_mfma_f32_16x16x32_bf16 v[52:55], v[150:153], v[170:173], v[52:55]
	v_mfma_f32_16x16x32_bf16 v[48:51], v[150:153], v[174:177], v[48:51]
	v_mfma_f32_16x16x32_bf16 v[44:47], v[150:153], v[180:183], v[44:47]
	v_mfma_f32_16x16x32_bf16 v[40:43], v[154:157], v[166:169], v[40:43]
	v_mfma_f32_16x16x32_bf16 v[36:39], v[154:157], v[170:173], v[36:39]
	v_mfma_f32_16x16x32_bf16 v[32:35], v[154:157], v[174:177], v[32:35]
	s_waitcnt vmcnt(0)
	s_barrier
	v_add3_u32 v198, v149, v147, s99
	v_add3_u32 v128, v149, v146, s99
	v_mfma_f32_16x16x32_bf16 v[28:31], v[154:157], v[180:183], v[28:31]
	ds_read_b128 v[186:189], v198 offset:32768
	ds_read_b128 v[190:193], v198 offset:34816
	v_mfma_f32_16x16x32_bf16 v[24:27], v[158:161], v[166:169], v[24:27]
	ds_read_b128 v[194:197], v198 offset:36864
	ds_read_b128 v[198:201], v198 offset:38912
	v_mfma_f32_16x16x32_bf16 v[20:23], v[158:161], v[170:173], v[20:23]
	ds_read_b128 v[202:205], v128 offset:0
	ds_read_b128 v[206:209], v128 offset:2048
	v_mfma_f32_16x16x32_bf16 v[16:19], v[158:161], v[174:177], v[16:19]
	ds_read_b128 v[210:213], v128 offset:4096
	ds_read_b128 v[214:217], v128 offset:6144
	s_mov_b32 m0, s4
	v_mfma_f32_16x16x32_bf16 v[12:15], v[158:161], v[180:183], v[12:15]
	global_load_lds_dwordx4 v[130:131], off
	v_lshl_add_u64 v[130:131], v[130:131], 0, s[100:101]
	s_add_i32 m0, s4, 0x8000
	v_mfma_f32_16x16x32_bf16 v[8:11], v[162:165], v[166:169], v[8:11]
	global_load_lds_dwordx4 v[138:139], off
	v_lshl_add_u64 v[138:139], v[138:139], 0, s[100:101]
	s_mov_b32 m0, s5
	v_mfma_f32_16x16x32_bf16 v[4:7], v[162:165], v[170:173], v[4:7]
	global_load_lds_dwordx4 v[132:133], off
	v_lshl_add_u64 v[132:133], v[132:133], 0, s[100:101]
	s_add_i32 m0, s5, 0x8000
	v_mfma_f32_16x16x32_bf16 v[0:3], v[162:165], v[174:177], v[0:3]
	global_load_lds_dwordx4 v[140:141], off
	v_lshl_add_u64 v[140:141], v[140:141], 0, s[100:101]
	s_mov_b32 m0, s6
	v_mfma_f32_16x16x32_bf16 v[88:91], v[162:165], v[180:183], v[88:91]
	global_load_lds_dwordx4 v[134:135], off
	v_lshl_add_u64 v[134:135], v[134:135], 0, s[100:101]
	s_add_i32 m0, s6, 0x8000
	s_nop 0
	global_load_lds_dwordx4 v[142:143], off
	v_lshl_add_u64 v[142:143], v[142:143], 0, s[100:101]
	s_mov_b32 m0, s7
	s_nop 0
	global_load_lds_dwordx4 v[136:137], off
	v_lshl_add_u64 v[136:137], v[136:137], 0, s[100:101]
	s_add_i32 m0, s7, 0x8000
	s_nop 0
	global_load_lds_dwordx4 v[144:145], off
	v_lshl_add_u64 v[144:145], v[144:145], 0, s[100:101]
	ds_read_b128 v[150:153], v128 offset:8192
	ds_read_b128 v[154:157], v128 offset:10240
	ds_read_b128 v[158:161], v128 offset:12288
	ds_read_b128 v[162:165], v128 offset:14336
	s_waitcnt lgkmcnt(4)
	v_mfma_f32_16x16x32_bf16 v[124:127], v[202:205], v[186:189], v[124:127]
	v_mfma_f32_16x16x32_bf16 v[120:123], v[202:205], v[190:193], v[120:123]
	v_mfma_f32_16x16x32_bf16 v[116:119], v[202:205], v[194:197], v[116:119]
	v_mfma_f32_16x16x32_bf16 v[112:115], v[202:205], v[198:201], v[112:115]
	v_mfma_f32_16x16x32_bf16 v[108:111], v[206:209], v[186:189], v[108:111]
	v_mfma_f32_16x16x32_bf16 v[104:107], v[206:209], v[190:193], v[104:107]
	v_mfma_f32_16x16x32_bf16 v[100:103], v[206:209], v[194:197], v[100:103]
	v_mfma_f32_16x16x32_bf16 v[96:99], v[206:209], v[198:201], v[96:99]
	v_mfma_f32_16x16x32_bf16 v[92:95], v[210:213], v[186:189], v[92:95]
	v_mfma_f32_16x16x32_bf16 v[84:87], v[210:213], v[190:193], v[84:87]
	v_mfma_f32_16x16x32_bf16 v[80:83], v[210:213], v[194:197], v[80:83]
	v_mfma_f32_16x16x32_bf16 v[76:79], v[210:213], v[198:201], v[76:79]
	v_mfma_f32_16x16x32_bf16 v[72:75], v[214:217], v[186:189], v[72:75]
	v_mfma_f32_16x16x32_bf16 v[68:71], v[214:217], v[190:193], v[68:71]
	v_mfma_f32_16x16x32_bf16 v[64:67], v[214:217], v[194:197], v[64:67]
	v_mfma_f32_16x16x32_bf16 v[60:63], v[214:217], v[198:201], v[60:63]
	v_add3_u32 v214, v148, v147, s99
	v_add3_u32 v128, v148, v146, s99
	ds_read_b128 v[202:205], v214 offset:32768
	ds_read_b128 v[206:209], v214 offset:34816
	ds_read_b128 v[210:213], v214 offset:36864
	ds_read_b128 v[214:217], v214 offset:38912
	ds_read_b128 v[166:169], v128 offset:0
	ds_read_b128 v[170:173], v128 offset:2048
	ds_read_b128 v[174:177], v128 offset:4096
	ds_read_b128 v[180:183], v128 offset:6144
	s_waitcnt lgkmcnt(8)
	v_mfma_f32_16x16x32_bf16 v[56:59], v[150:153], v[186:189], v[56:59]
	v_mfma_f32_16x16x32_bf16 v[52:55], v[150:153], v[190:193], v[52:55]
	v_mfma_f32_16x16x32_bf16 v[48:51], v[150:153], v[194:197], v[48:51]
	v_mfma_f32_16x16x32_bf16 v[44:47], v[150:153], v[198:201], v[44:47]
	v_mfma_f32_16x16x32_bf16 v[40:43], v[154:157], v[186:189], v[40:43]
	v_mfma_f32_16x16x32_bf16 v[36:39], v[154:157], v[190:193], v[36:39]
	v_mfma_f32_16x16x32_bf16 v[32:35], v[154:157], v[194:197], v[32:35]
	v_mfma_f32_16x16x32_bf16 v[28:31], v[154:157], v[198:201], v[28:31]
	v_mfma_f32_16x16x32_bf16 v[24:27], v[158:161], v[186:189], v[24:27]
	v_mfma_f32_16x16x32_bf16 v[20:23], v[158:161], v[190:193], v[20:23]
	v_mfma_f32_16x16x32_bf16 v[16:19], v[158:161], v[194:197], v[16:19]
	v_mfma_f32_16x16x32_bf16 v[12:15], v[158:161], v[198:201], v[12:15]
	v_mfma_f32_16x16x32_bf16 v[8:11], v[162:165], v[186:189], v[8:11]
	v_mfma_f32_16x16x32_bf16 v[4:7], v[162:165], v[190:193], v[4:7]
	v_mfma_f32_16x16x32_bf16 v[0:3], v[162:165], v[194:197], v[0:3]
	v_mfma_f32_16x16x32_bf16 v[88:91], v[162:165], v[198:201], v[88:91]
	ds_read_b128 v[186:189], v128 offset:8192
	ds_read_b128 v[190:193], v128 offset:10240
	ds_read_b128 v[194:197], v128 offset:12288
	ds_read_b128 v[198:201], v128 offset:14336
	s_waitcnt lgkmcnt(4)
	v_mfma_f32_16x16x32_bf16 v[124:127], v[166:169], v[202:205], v[124:127]
	v_mfma_f32_16x16x32_bf16 v[120:123], v[166:169], v[206:209], v[120:123]
	v_mfma_f32_16x16x32_bf16 v[116:119], v[166:169], v[210:213], v[116:119]
	v_mfma_f32_16x16x32_bf16 v[112:115], v[166:169], v[214:217], v[112:115]
	v_mfma_f32_16x16x32_bf16 v[108:111], v[170:173], v[202:205], v[108:111]
	v_mfma_f32_16x16x32_bf16 v[104:107], v[170:173], v[206:209], v[104:107]
	v_mfma_f32_16x16x32_bf16 v[100:103], v[170:173], v[210:213], v[100:103]
	v_mfma_f32_16x16x32_bf16 v[96:99], v[170:173], v[214:217], v[96:99]
	v_mfma_f32_16x16x32_bf16 v[92:95], v[174:177], v[202:205], v[92:95]
	v_mfma_f32_16x16x32_bf16 v[84:87], v[174:177], v[206:209], v[84:87]
	v_mfma_f32_16x16x32_bf16 v[80:83], v[174:177], v[210:213], v[80:83]
	v_mfma_f32_16x16x32_bf16 v[76:79], v[174:177], v[214:217], v[76:79]
	v_mfma_f32_16x16x32_bf16 v[72:75], v[180:183], v[202:205], v[72:75]
	v_mfma_f32_16x16x32_bf16 v[68:71], v[180:183], v[206:209], v[68:71]
	v_mfma_f32_16x16x32_bf16 v[64:67], v[180:183], v[210:213], v[64:67]
	v_mfma_f32_16x16x32_bf16 v[60:63], v[180:183], v[214:217], v[60:63]
	s_waitcnt lgkmcnt(0)
	v_mfma_f32_16x16x32_bf16 v[56:59], v[186:189], v[202:205], v[56:59]
	v_mfma_f32_16x16x32_bf16 v[52:55], v[186:189], v[206:209], v[52:55]
	v_mfma_f32_16x16x32_bf16 v[48:51], v[186:189], v[210:213], v[48:51]
	v_mfma_f32_16x16x32_bf16 v[44:47], v[186:189], v[214:217], v[44:47]
	v_mfma_f32_16x16x32_bf16 v[40:43], v[190:193], v[202:205], v[40:43]
	v_mfma_f32_16x16x32_bf16 v[36:39], v[190:193], v[206:209], v[36:39]
	v_mfma_f32_16x16x32_bf16 v[32:35], v[190:193], v[210:213], v[32:35]
	s_waitcnt vmcnt(0)
	s_barrier
	v_add_u32_e32 v162, v149, v147
	v_add_u32_e32 v128, v149, v146
	v_mfma_f32_16x16x32_bf16 v[28:31], v[190:193], v[214:217], v[28:31]
	ds_read_b128 v[150:153], v162 offset:32768
	ds_read_b128 v[154:157], v162 offset:34816
	v_mfma_f32_16x16x32_bf16 v[24:27], v[194:197], v[202:205], v[24:27]
	ds_read_b128 v[158:161], v162 offset:36864
	ds_read_b128 v[162:165], v162 offset:38912
	v_mfma_f32_16x16x32_bf16 v[20:23], v[194:197], v[206:209], v[20:23]
	ds_read_b128 v[166:169], v128 offset:0
	ds_read_b128 v[170:173], v128 offset:2048
	v_mfma_f32_16x16x32_bf16 v[16:19], v[194:197], v[210:213], v[16:19]
	ds_read_b128 v[174:177], v128 offset:4096
	ds_read_b128 v[180:183], v128 offset:6144
	s_add_i32 m0, s4, 0x10000
	v_mfma_f32_16x16x32_bf16 v[12:15], v[194:197], v[214:217], v[12:15]
	global_load_lds_dwordx4 v[130:131], off
	v_lshl_add_u64 v[130:131], v[130:131], 0, s[100:101]
	s_add_i32 m0, s4, 0x18000
	v_mfma_f32_16x16x32_bf16 v[8:11], v[198:201], v[202:205], v[8:11]
	global_load_lds_dwordx4 v[138:139], off
	v_lshl_add_u64 v[138:139], v[138:139], 0, s[100:101]
	s_add_i32 m0, s5, 0x10000
	v_mfma_f32_16x16x32_bf16 v[4:7], v[198:201], v[206:209], v[4:7]
	global_load_lds_dwordx4 v[132:133], off
	v_lshl_add_u64 v[132:133], v[132:133], 0, s[100:101]
	s_add_i32 m0, s5, 0x18000
	v_mfma_f32_16x16x32_bf16 v[0:3], v[198:201], v[210:213], v[0:3]
	global_load_lds_dwordx4 v[140:141], off
	v_lshl_add_u64 v[140:141], v[140:141], 0, s[100:101]
	s_add_i32 m0, s6, 0x10000
	v_mfma_f32_16x16x32_bf16 v[88:91], v[198:201], v[214:217], v[88:91]
	global_load_lds_dwordx4 v[134:135], off
	v_lshl_add_u64 v[134:135], v[134:135], 0, s[100:101]
	s_add_i32 m0, s6, 0x18000
	s_nop 0
	global_load_lds_dwordx4 v[142:143], off
	v_lshl_add_u64 v[142:143], v[142:143], 0, s[100:101]
	s_add_i32 m0, s7, 0x10000
	s_nop 0
	global_load_lds_dwordx4 v[136:137], off
	v_lshl_add_u64 v[136:137], v[136:137], 0, s[100:101]
	s_add_i32 m0, s7, 0x18000
	s_nop 0
	global_load_lds_dwordx4 v[144:145], off
	v_lshl_add_u64 v[144:145], v[144:145], 0, s[100:101]
	s_movk_i32 s2, 0x100
.Lg_inproj_loop:
	ds_read_b128 v[186:189], v128 offset:8192
	ds_read_b128 v[190:193], v128 offset:10240
	ds_read_b128 v[194:197], v128 offset:12288
	ds_read_b128 v[198:201], v128 offset:14336
	s_waitcnt lgkmcnt(4)
	v_mfma_f32_16x16x32_bf16 v[124:127], v[166:169], v[150:153], v[124:127]
	v_mfma_f32_16x16x32_bf16 v[120:123], v[166:169], v[154:157], v[120:123]
	v_mfma_f32_16x16x32_bf16 v[116:119], v[166:169], v[158:161], v[116:119]
	v_mfma_f32_16x16x32_bf16 v[112:115], v[166:169], v[162:165], v[112:115]
	v_mfma_f32_16x16x32_bf16 v[108:111], v[170:173], v[150:153], v[108:111]
	v_mfma_f32_16x16x32_bf16 v[104:107], v[170:173], v[154:157], v[104:107]
	v_mfma_f32_16x16x32_bf16 v[100:103], v[170:173], v[158:161], v[100:103]
	v_mfma_f32_16x16x32_bf16 v[96:99], v[170:173], v[162:165], v[96:99]
	v_mfma_f32_16x16x32_bf16 v[92:95], v[174:177], v[150:153], v[92:95]
	v_mfma_f32_16x16x32_bf16 v[84:87], v[174:177], v[154:157], v[84:87]
	v_mfma_f32_16x16x32_bf16 v[80:83], v[174:177], v[158:161], v[80:83]
	v_mfma_f32_16x16x32_bf16 v[76:79], v[174:177], v[162:165], v[76:79]
	v_mfma_f32_16x16x32_bf16 v[72:75], v[180:183], v[150:153], v[72:75]
	v_mfma_f32_16x16x32_bf16 v[68:71], v[180:183], v[154:157], v[68:71]
	v_mfma_f32_16x16x32_bf16 v[64:67], v[180:183], v[158:161], v[64:67]
	v_mfma_f32_16x16x32_bf16 v[60:63], v[180:183], v[162:165], v[60:63]
	v_add_u32_e32 v180, v148, v147
	v_add_u32_e32 v128, v148, v146
	ds_read_b128 v[166:169], v180 offset:32768
	ds_read_b128 v[170:173], v180 offset:34816
	ds_read_b128 v[174:177], v180 offset:36864
	ds_read_b128 v[180:183], v180 offset:38912
	ds_read_b128 v[202:205], v128 offset:0
	ds_read_b128 v[206:209], v128 offset:2048
	ds_read_b128 v[210:213], v128 offset:4096
	ds_read_b128 v[214:217], v128 offset:6144
	s_waitcnt lgkmcnt(8)
	v_mfma_f32_16x16x32_bf16 v[56:59], v[186:189], v[150:153], v[56:59]
	v_mfma_f32_16x16x32_bf16 v[52:55], v[186:189], v[154:157], v[52:55]
	v_mfma_f32_16x16x32_bf16 v[48:51], v[186:189], v[158:161], v[48:51]
	v_mfma_f32_16x16x32_bf16 v[44:47], v[186:189], v[162:165], v[44:47]
	v_mfma_f32_16x16x32_bf16 v[40:43], v[190:193], v[150:153], v[40:43]
	v_mfma_f32_16x16x32_bf16 v[36:39], v[190:193], v[154:157], v[36:39]
	v_mfma_f32_16x16x32_bf16 v[32:35], v[190:193], v[158:161], v[32:35]
	v_mfma_f32_16x16x32_bf16 v[28:31], v[190:193], v[162:165], v[28:31]
	v_mfma_f32_16x16x32_bf16 v[24:27], v[194:197], v[150:153], v[24:27]
	v_mfma_f32_16x16x32_bf16 v[20:23], v[194:197], v[154:157], v[20:23]
	v_mfma_f32_16x16x32_bf16 v[16:19], v[194:197], v[158:161], v[16:19]
	v_mfma_f32_16x16x32_bf16 v[12:15], v[194:197], v[162:165], v[12:15]
	v_mfma_f32_16x16x32_bf16 v[8:11], v[198:201], v[150:153], v[8:11]
	v_mfma_f32_16x16x32_bf16 v[4:7], v[198:201], v[154:157], v[4:7]
	v_mfma_f32_16x16x32_bf16 v[0:3], v[198:201], v[158:161], v[0:3]
	v_mfma_f32_16x16x32_bf16 v[88:91], v[198:201], v[162:165], v[88:91]
	ds_read_b128 v[150:153], v128 offset:8192
	ds_read_b128 v[154:157], v128 offset:10240
	ds_read_b128 v[158:161], v128 offset:12288
	ds_read_b128 v[162:165], v128 offset:14336
	s_waitcnt lgkmcnt(4)
	v_mfma_f32_16x16x32_bf16 v[124:127], v[202:205], v[166:169], v[124:127]
	v_mfma_f32_16x16x32_bf16 v[120:123], v[202:205], v[170:173], v[120:123]
	v_mfma_f32_16x16x32_bf16 v[116:119], v[202:205], v[174:177], v[116:119]
	v_mfma_f32_16x16x32_bf16 v[112:115], v[202:205], v[180:183], v[112:115]
	v_mfma_f32_16x16x32_bf16 v[108:111], v[206:209], v[166:169], v[108:111]
	v_mfma_f32_16x16x32_bf16 v[104:107], v[206:209], v[170:173], v[104:107]
	v_mfma_f32_16x16x32_bf16 v[100:103], v[206:209], v[174:177], v[100:103]
	v_mfma_f32_16x16x32_bf16 v[96:99], v[206:209], v[180:183], v[96:99]
	v_mfma_f32_16x16x32_bf16 v[92:95], v[210:213], v[166:169], v[92:95]
	v_mfma_f32_16x16x32_bf16 v[84:87], v[210:213], v[170:173], v[84:87]
	v_mfma_f32_16x16x32_bf16 v[80:83], v[210:213], v[174:177], v[80:83]
	v_mfma_f32_16x16x32_bf16 v[76:79], v[210:213], v[180:183], v[76:79]
	v_mfma_f32_16x16x32_bf16 v[72:75], v[214:217], v[166:169], v[72:75]
	v_mfma_f32_16x16x32_bf16 v[68:71], v[214:217], v[170:173], v[68:71]
	v_mfma_f32_16x16x32_bf16 v[64:67], v[214:217], v[174:177], v[64:67]
	v_mfma_f32_16x16x32_bf16 v[60:63], v[214:217], v[180:183], v[60:63]
	s_waitcnt lgkmcnt(0)
	v_mfma_f32_16x16x32_bf16 v[56:59], v[150:153], v[166:169], v[56:59]
	v_mfma_f32_16x16x32_bf16 v[52:55], v[150:153], v[170:173], v[52:55]
	v_mfma_f32_16x16x32_bf16 v[48:51], v[150:153], v[174:177], v[48:51]
	v_mfma_f32_16x16x32_bf16 v[44:47], v[150:153], v[180:183], v[44:47]
	v_mfma_f32_16x16x32_bf16 v[40:43], v[154:157], v[166:169], v[40:43]
	v_mfma_f32_16x16x32_bf16 v[36:39], v[154:157], v[170:173], v[36:39]
	v_mfma_f32_16x16x32_bf16 v[32:35], v[154:157], v[174:177], v[32:35]
	s_waitcnt vmcnt(0)
	s_barrier
	v_add3_u32 v198, v149, v147, s99
	v_add3_u32 v128, v149, v146, s99
	v_mfma_f32_16x16x32_bf16 v[28:31], v[154:157], v[180:183], v[28:31]
	ds_read_b128 v[186:189], v198 offset:32768
	ds_read_b128 v[190:193], v198 offset:34816
	v_mfma_f32_16x16x32_bf16 v[24:27], v[158:161], v[166:169], v[24:27]
	ds_read_b128 v[194:197], v198 offset:36864
	ds_read_b128 v[198:201], v198 offset:38912
	v_mfma_f32_16x16x32_bf16 v[20:23], v[158:161], v[170:173], v[20:23]
	ds_read_b128 v[202:205], v128 offset:0
	ds_read_b128 v[206:209], v128 offset:2048
	v_mfma_f32_16x16x32_bf16 v[16:19], v[158:161], v[174:177], v[16:19]
	ds_read_b128 v[210:213], v128 offset:4096
	ds_read_b128 v[214:217], v128 offset:6144
	s_mov_b32 m0, s4
	v_mfma_f32_16x16x32_bf16 v[12:15], v[158:161], v[180:183], v[12:15]
	global_load_lds_dwordx4 v[130:131], off
	v_lshl_add_u64 v[130:131], v[130:131], 0, s[100:101]
	s_add_i32 m0, s4, 0x8000
	v_mfma_f32_16x16x32_bf16 v[8:11], v[162:165], v[166:169], v[8:11]
	global_load_lds_dwordx4 v[138:139], off
	v_lshl_add_u64 v[138:139], v[138:139], 0, s[100:101]
	s_mov_b32 m0, s5
	v_mfma_f32_16x16x32_bf16 v[4:7], v[162:165], v[170:173], v[4:7]
	global_load_lds_dwordx4 v[132:133], off
	v_lshl_add_u64 v[132:133], v[132:133], 0, s[100:101]
	s_add_i32 m0, s5, 0x8000
	v_mfma_f32_16x16x32_bf16 v[0:3], v[162:165], v[174:177], v[0:3]
	global_load_lds_dwordx4 v[140:141], off
	v_lshl_add_u64 v[140:141], v[140:141], 0, s[100:101]
	s_mov_b32 m0, s6
	v_mfma_f32_16x16x32_bf16 v[88:91], v[162:165], v[180:183], v[88:91]
	global_load_lds_dwordx4 v[134:135], off
	v_lshl_add_u64 v[134:135], v[134:135], 0, s[100:101]
	s_add_i32 m0, s6, 0x8000
	s_nop 0
	global_load_lds_dwordx4 v[142:143], off
	v_lshl_add_u64 v[142:143], v[142:143], 0, s[100:101]
	s_mov_b32 m0, s7
	s_nop 0
	global_load_lds_dwordx4 v[136:137], off
	v_lshl_add_u64 v[136:137], v[136:137], 0, s[100:101]
	s_add_i32 m0, s7, 0x8000
	s_nop 0
	global_load_lds_dwordx4 v[144:145], off
	v_lshl_add_u64 v[144:145], v[144:145], 0, s[100:101]
	ds_read_b128 v[150:153], v128 offset:8192
	ds_read_b128 v[154:157], v128 offset:10240
	ds_read_b128 v[158:161], v128 offset:12288
	ds_read_b128 v[162:165], v128 offset:14336
	s_waitcnt lgkmcnt(4)
	v_mfma_f32_16x16x32_bf16 v[124:127], v[202:205], v[186:189], v[124:127]
	v_mfma_f32_16x16x32_bf16 v[120:123], v[202:205], v[190:193], v[120:123]
	v_mfma_f32_16x16x32_bf16 v[116:119], v[202:205], v[194:197], v[116:119]
	v_mfma_f32_16x16x32_bf16 v[112:115], v[202:205], v[198:201], v[112:115]
	v_mfma_f32_16x16x32_bf16 v[108:111], v[206:209], v[186:189], v[108:111]
	v_mfma_f32_16x16x32_bf16 v[104:107], v[206:209], v[190:193], v[104:107]
	v_mfma_f32_16x16x32_bf16 v[100:103], v[206:209], v[194:197], v[100:103]
	v_mfma_f32_16x16x32_bf16 v[96:99], v[206:209], v[198:201], v[96:99]
	v_mfma_f32_16x16x32_bf16 v[92:95], v[210:213], v[186:189], v[92:95]
	v_mfma_f32_16x16x32_bf16 v[84:87], v[210:213], v[190:193], v[84:87]
	v_mfma_f32_16x16x32_bf16 v[80:83], v[210:213], v[194:197], v[80:83]
	v_mfma_f32_16x16x32_bf16 v[76:79], v[210:213], v[198:201], v[76:79]
	v_mfma_f32_16x16x32_bf16 v[72:75], v[214:217], v[186:189], v[72:75]
	v_mfma_f32_16x16x32_bf16 v[68:71], v[214:217], v[190:193], v[68:71]
	v_mfma_f32_16x16x32_bf16 v[64:67], v[214:217], v[194:197], v[64:67]
	v_mfma_f32_16x16x32_bf16 v[60:63], v[214:217], v[198:201], v[60:63]
	v_add3_u32 v214, v148, v147, s99
	v_add3_u32 v128, v148, v146, s99
	ds_read_b128 v[202:205], v214 offset:32768
	ds_read_b128 v[206:209], v214 offset:34816
	ds_read_b128 v[210:213], v214 offset:36864
	ds_read_b128 v[214:217], v214 offset:38912
	ds_read_b128 v[166:169], v128 offset:0
	ds_read_b128 v[170:173], v128 offset:2048
	ds_read_b128 v[174:177], v128 offset:4096
	ds_read_b128 v[180:183], v128 offset:6144
	s_waitcnt lgkmcnt(8)
	v_mfma_f32_16x16x32_bf16 v[56:59], v[150:153], v[186:189], v[56:59]
	v_mfma_f32_16x16x32_bf16 v[52:55], v[150:153], v[190:193], v[52:55]
	v_mfma_f32_16x16x32_bf16 v[48:51], v[150:153], v[194:197], v[48:51]
	v_mfma_f32_16x16x32_bf16 v[44:47], v[150:153], v[198:201], v[44:47]
	v_mfma_f32_16x16x32_bf16 v[40:43], v[154:157], v[186:189], v[40:43]
	v_mfma_f32_16x16x32_bf16 v[36:39], v[154:157], v[190:193], v[36:39]
	v_mfma_f32_16x16x32_bf16 v[32:35], v[154:157], v[194:197], v[32:35]
	v_mfma_f32_16x16x32_bf16 v[28:31], v[154:157], v[198:201], v[28:31]
	v_mfma_f32_16x16x32_bf16 v[24:27], v[158:161], v[186:189], v[24:27]
	v_mfma_f32_16x16x32_bf16 v[20:23], v[158:161], v[190:193], v[20:23]
	v_mfma_f32_16x16x32_bf16 v[16:19], v[158:161], v[194:197], v[16:19]
	v_mfma_f32_16x16x32_bf16 v[12:15], v[158:161], v[198:201], v[12:15]
	v_mfma_f32_16x16x32_bf16 v[8:11], v[162:165], v[186:189], v[8:11]
	v_mfma_f32_16x16x32_bf16 v[4:7], v[162:165], v[190:193], v[4:7]
	v_mfma_f32_16x16x32_bf16 v[0:3], v[162:165], v[194:197], v[0:3]
	v_mfma_f32_16x16x32_bf16 v[88:91], v[162:165], v[198:201], v[88:91]
	ds_read_b128 v[186:189], v128 offset:8192
	ds_read_b128 v[190:193], v128 offset:10240
	ds_read_b128 v[194:197], v128 offset:12288
	ds_read_b128 v[198:201], v128 offset:14336
	s_waitcnt lgkmcnt(4)
	v_mfma_f32_16x16x32_bf16 v[124:127], v[166:169], v[202:205], v[124:127]
	v_mfma_f32_16x16x32_bf16 v[120:123], v[166:169], v[206:209], v[120:123]
	v_mfma_f32_16x16x32_bf16 v[116:119], v[166:169], v[210:213], v[116:119]
	v_mfma_f32_16x16x32_bf16 v[112:115], v[166:169], v[214:217], v[112:115]
	v_mfma_f32_16x16x32_bf16 v[108:111], v[170:173], v[202:205], v[108:111]
	v_mfma_f32_16x16x32_bf16 v[104:107], v[170:173], v[206:209], v[104:107]
	v_mfma_f32_16x16x32_bf16 v[100:103], v[170:173], v[210:213], v[100:103]
	v_mfma_f32_16x16x32_bf16 v[96:99], v[170:173], v[214:217], v[96:99]
	v_mfma_f32_16x16x32_bf16 v[92:95], v[174:177], v[202:205], v[92:95]
	v_mfma_f32_16x16x32_bf16 v[84:87], v[174:177], v[206:209], v[84:87]
	v_mfma_f32_16x16x32_bf16 v[80:83], v[174:177], v[210:213], v[80:83]
	v_mfma_f32_16x16x32_bf16 v[76:79], v[174:177], v[214:217], v[76:79]
	v_mfma_f32_16x16x32_bf16 v[72:75], v[180:183], v[202:205], v[72:75]
	v_mfma_f32_16x16x32_bf16 v[68:71], v[180:183], v[206:209], v[68:71]
	v_mfma_f32_16x16x32_bf16 v[64:67], v[180:183], v[210:213], v[64:67]
	v_mfma_f32_16x16x32_bf16 v[60:63], v[180:183], v[214:217], v[60:63]
	s_waitcnt lgkmcnt(0)
	v_mfma_f32_16x16x32_bf16 v[56:59], v[186:189], v[202:205], v[56:59]
	v_mfma_f32_16x16x32_bf16 v[52:55], v[186:189], v[206:209], v[52:55]
	v_mfma_f32_16x16x32_bf16 v[48:51], v[186:189], v[210:213], v[48:51]
	v_mfma_f32_16x16x32_bf16 v[44:47], v[186:189], v[214:217], v[44:47]
	v_mfma_f32_16x16x32_bf16 v[40:43], v[190:193], v[202:205], v[40:43]
	v_mfma_f32_16x16x32_bf16 v[36:39], v[190:193], v[206:209], v[36:39]
	v_mfma_f32_16x16x32_bf16 v[32:35], v[190:193], v[210:213], v[32:35]
	s_waitcnt vmcnt(0)
	s_barrier
	v_add_u32_e32 v162, v149, v147
	v_add_u32_e32 v128, v149, v146
	v_mfma_f32_16x16x32_bf16 v[28:31], v[190:193], v[214:217], v[28:31]
	ds_read_b128 v[150:153], v162 offset:32768
	ds_read_b128 v[154:157], v162 offset:34816
	v_mfma_f32_16x16x32_bf16 v[24:27], v[194:197], v[202:205], v[24:27]
	ds_read_b128 v[158:161], v162 offset:36864
	ds_read_b128 v[162:165], v162 offset:38912
	v_mfma_f32_16x16x32_bf16 v[20:23], v[194:197], v[206:209], v[20:23]
	ds_read_b128 v[166:169], v128 offset:0
	ds_read_b128 v[170:173], v128 offset:2048
	v_mfma_f32_16x16x32_bf16 v[16:19], v[194:197], v[210:213], v[16:19]
	ds_read_b128 v[174:177], v128 offset:4096
	ds_read_b128 v[180:183], v128 offset:6144
	s_add_i32 m0, s4, 0x10000
	v_mfma_f32_16x16x32_bf16 v[12:15], v[194:197], v[214:217], v[12:15]
	global_load_lds_dwordx4 v[130:131], off
	v_lshl_add_u64 v[130:131], v[130:131], 0, s[100:101]
	s_add_i32 m0, s4, 0x18000
	v_mfma_f32_16x16x32_bf16 v[8:11], v[198:201], v[202:205], v[8:11]
	global_load_lds_dwordx4 v[138:139], off
	v_lshl_add_u64 v[138:139], v[138:139], 0, s[100:101]
	s_add_i32 m0, s5, 0x10000
	v_mfma_f32_16x16x32_bf16 v[4:7], v[198:201], v[206:209], v[4:7]
	global_load_lds_dwordx4 v[132:133], off
	v_lshl_add_u64 v[132:133], v[132:133], 0, s[100:101]
	s_add_i32 m0, s5, 0x18000
	v_mfma_f32_16x16x32_bf16 v[0:3], v[198:201], v[210:213], v[0:3]
	global_load_lds_dwordx4 v[140:141], off
	v_lshl_add_u64 v[140:141], v[140:141], 0, s[100:101]
	s_add_i32 m0, s6, 0x10000
	v_mfma_f32_16x16x32_bf16 v[88:91], v[198:201], v[214:217], v[88:91]
	global_load_lds_dwordx4 v[134:135], off
	v_lshl_add_u64 v[134:135], v[134:135], 0, s[100:101]
	s_add_i32 m0, s6, 0x18000
	s_nop 0
	global_load_lds_dwordx4 v[142:143], off
	v_lshl_add_u64 v[142:143], v[142:143], 0, s[100:101]
	s_add_i32 m0, s7, 0x10000
	s_nop 0
	global_load_lds_dwordx4 v[136:137], off
	v_lshl_add_u64 v[136:137], v[136:137], 0, s[100:101]
	s_add_i32 m0, s7, 0x18000
	s_nop 0
	global_load_lds_dwordx4 v[144:145], off
	v_lshl_add_u64 v[144:145], v[144:145], 0, s[100:101]
	s_add_u32 s2, s2, 0x100
	s_cmpk_lg_i32 s2, 0x700
	s_cbranch_scc1 .Lg_inproj_loop
	ds_read_b128 v[186:189], v128 offset:8192
	ds_read_b128 v[190:193], v128 offset:10240
	ds_read_b128 v[194:197], v128 offset:12288
	ds_read_b128 v[198:201], v128 offset:14336
	s_waitcnt lgkmcnt(4)
	v_mfma_f32_16x16x32_bf16 v[124:127], v[166:169], v[150:153], v[124:127]
	v_mfma_f32_16x16x32_bf16 v[120:123], v[166:169], v[154:157], v[120:123]
	v_mfma_f32_16x16x32_bf16 v[116:119], v[166:169], v[158:161], v[116:119]
	v_mfma_f32_16x16x32_bf16 v[112:115], v[166:169], v[162:165], v[112:115]
	v_mfma_f32_16x16x32_bf16 v[108:111], v[170:173], v[150:153], v[108:111]
	v_mfma_f32_16x16x32_bf16 v[104:107], v[170:173], v[154:157], v[104:107]
	v_mfma_f32_16x16x32_bf16 v[100:103], v[170:173], v[158:161], v[100:103]
	v_mfma_f32_16x16x32_bf16 v[96:99], v[170:173], v[162:165], v[96:99]
	v_mfma_f32_16x16x32_bf16 v[92:95], v[174:177], v[150:153], v[92:95]
	v_mfma_f32_16x16x32_bf16 v[84:87], v[174:177], v[154:157], v[84:87]
	v_mfma_f32_16x16x32_bf16 v[80:83], v[174:177], v[158:161], v[80:83]
	v_mfma_f32_16x16x32_bf16 v[76:79], v[174:177], v[162:165], v[76:79]
	v_mfma_f32_16x16x32_bf16 v[72:75], v[180:183], v[150:153], v[72:75]
	v_mfma_f32_16x16x32_bf16 v[68:71], v[180:183], v[154:157], v[68:71]
	v_mfma_f32_16x16x32_bf16 v[64:67], v[180:183], v[158:161], v[64:67]
	v_mfma_f32_16x16x32_bf16 v[60:63], v[180:183], v[162:165], v[60:63]
	v_add_u32_e32 v180, v148, v147
	v_add_u32_e32 v128, v148, v146
	ds_read_b128 v[166:169], v180 offset:32768
	ds_read_b128 v[170:173], v180 offset:34816
	ds_read_b128 v[174:177], v180 offset:36864
	ds_read_b128 v[180:183], v180 offset:38912
	ds_read_b128 v[202:205], v128 offset:0
	ds_read_b128 v[206:209], v128 offset:2048
	ds_read_b128 v[210:213], v128 offset:4096
	ds_read_b128 v[214:217], v128 offset:6144
	s_waitcnt lgkmcnt(8)
	v_mfma_f32_16x16x32_bf16 v[56:59], v[186:189], v[150:153], v[56:59]
	v_mfma_f32_16x16x32_bf16 v[52:55], v[186:189], v[154:157], v[52:55]
	v_mfma_f32_16x16x32_bf16 v[48:51], v[186:189], v[158:161], v[48:51]
	v_mfma_f32_16x16x32_bf16 v[44:47], v[186:189], v[162:165], v[44:47]
	v_mfma_f32_16x16x32_bf16 v[40:43], v[190:193], v[150:153], v[40:43]
	v_mfma_f32_16x16x32_bf16 v[36:39], v[190:193], v[154:157], v[36:39]
	v_mfma_f32_16x16x32_bf16 v[32:35], v[190:193], v[158:161], v[32:35]
	v_mfma_f32_16x16x32_bf16 v[28:31], v[190:193], v[162:165], v[28:31]
	v_mfma_f32_16x16x32_bf16 v[24:27], v[194:197], v[150:153], v[24:27]
	v_mfma_f32_16x16x32_bf16 v[20:23], v[194:197], v[154:157], v[20:23]
	v_mfma_f32_16x16x32_bf16 v[16:19], v[194:197], v[158:161], v[16:19]
	v_mfma_f32_16x16x32_bf16 v[12:15], v[194:197], v[162:165], v[12:15]
	v_mfma_f32_16x16x32_bf16 v[8:11], v[198:201], v[150:153], v[8:11]
	v_mfma_f32_16x16x32_bf16 v[4:7], v[198:201], v[154:157], v[4:7]
	v_mfma_f32_16x16x32_bf16 v[0:3], v[198:201], v[158:161], v[0:3]
	v_mfma_f32_16x16x32_bf16 v[88:91], v[198:201], v[162:165], v[88:91]
	ds_read_b128 v[150:153], v128 offset:8192
	ds_read_b128 v[154:157], v128 offset:10240
	ds_read_b128 v[158:161], v128 offset:12288
	ds_read_b128 v[162:165], v128 offset:14336
	s_waitcnt lgkmcnt(4)
	v_mfma_f32_16x16x32_bf16 v[124:127], v[202:205], v[166:169], v[124:127]
	v_mfma_f32_16x16x32_bf16 v[120:123], v[202:205], v[170:173], v[120:123]
	v_mfma_f32_16x16x32_bf16 v[116:119], v[202:205], v[174:177], v[116:119]
	v_mfma_f32_16x16x32_bf16 v[112:115], v[202:205], v[180:183], v[112:115]
	v_mfma_f32_16x16x32_bf16 v[108:111], v[206:209], v[166:169], v[108:111]
	v_mfma_f32_16x16x32_bf16 v[104:107], v[206:209], v[170:173], v[104:107]
	v_mfma_f32_16x16x32_bf16 v[100:103], v[206:209], v[174:177], v[100:103]
	v_mfma_f32_16x16x32_bf16 v[96:99], v[206:209], v[180:183], v[96:99]
	v_mfma_f32_16x16x32_bf16 v[92:95], v[210:213], v[166:169], v[92:95]
	v_mfma_f32_16x16x32_bf16 v[84:87], v[210:213], v[170:173], v[84:87]
	v_mfma_f32_16x16x32_bf16 v[80:83], v[210:213], v[174:177], v[80:83]
	v_mfma_f32_16x16x32_bf16 v[76:79], v[210:213], v[180:183], v[76:79]
	v_mfma_f32_16x16x32_bf16 v[72:75], v[214:217], v[166:169], v[72:75]
	v_mfma_f32_16x16x32_bf16 v[68:71], v[214:217], v[170:173], v[68:71]
	v_mfma_f32_16x16x32_bf16 v[64:67], v[214:217], v[174:177], v[64:67]
	v_mfma_f32_16x16x32_bf16 v[60:63], v[214:217], v[180:183], v[60:63]
	s_waitcnt lgkmcnt(0)
	v_mfma_f32_16x16x32_bf16 v[56:59], v[150:153], v[166:169], v[56:59]
	v_mfma_f32_16x16x32_bf16 v[52:55], v[150:153], v[170:173], v[52:55]
	v_mfma_f32_16x16x32_bf16 v[48:51], v[150:153], v[174:177], v[48:51]
	v_mfma_f32_16x16x32_bf16 v[44:47], v[150:153], v[180:183], v[44:47]
	v_mfma_f32_16x16x32_bf16 v[40:43], v[154:157], v[166:169], v[40:43]
	v_mfma_f32_16x16x32_bf16 v[36:39], v[154:157], v[170:173], v[36:39]
	v_mfma_f32_16x16x32_bf16 v[32:35], v[154:157], v[174:177], v[32:35]
	s_waitcnt vmcnt(0)
	s_barrier
	v_mfma_f32_16x16x32_bf16 v[28:31], v[154:157], v[180:183], v[28:31]
	v_mfma_f32_16x16x32_bf16 v[24:27], v[158:161], v[166:169], v[24:27]
	v_mfma_f32_16x16x32_bf16 v[20:23], v[158:161], v[170:173], v[20:23]
	v_mfma_f32_16x16x32_bf16 v[16:19], v[158:161], v[174:177], v[16:19]
	v_mfma_f32_16x16x32_bf16 v[12:15], v[158:161], v[180:183], v[12:15]
	v_mfma_f32_16x16x32_bf16 v[8:11], v[162:165], v[166:169], v[8:11]
	v_mfma_f32_16x16x32_bf16 v[4:7], v[162:165], v[170:173], v[4:7]
	v_mfma_f32_16x16x32_bf16 v[0:3], v[162:165], v[174:177], v[0:3]
	v_mfma_f32_16x16x32_bf16 v[88:91], v[162:165], v[180:183], v[88:91]
	s_movk_i32 s2, 0x780
	s_mov_b32 s8, 0xf0000
	s_mov_b32 s10, 0xf0000
	s_mov_b32 s9, 0x10000
	s_add_i32 s11, s7, 0x10000
	v_add_u32_e32 v128, s9, v149
	v_add_u32_e32 v142, v128, v147
	v_add_u32_e32 v128, v128, v146
	ds_read_b128 v[130:133], v142 offset:32768
	ds_read_b128 v[134:137], v142 offset:34816
	ds_read_b128 v[138:141], v142 offset:36864
	ds_read_b128 v[142:145], v142 offset:38912
	ds_read_b128 v[150:153], v128
	ds_read_b128 v[154:157], v128 offset:2048
	ds_read_b128 v[158:161], v128 offset:4096
	ds_read_b128 v[162:165], v128 offset:6144
	ds_read_b128 v[166:169], v128 offset:8192
	ds_read_b128 v[170:173], v128 offset:10240
	ds_read_b128 v[174:177], v128 offset:12288
	ds_read_b128 v[180:183], v128 offset:14336
	s_lshl_b32 s31, s28, 8
	s_lshl_b32 s4, s30, 8
	s_waitcnt lgkmcnt(0)
	v_mfma_f32_16x16x32_bf16 v[124:127], v[150:153], v[130:133], v[124:127]
	v_mfma_f32_16x16x32_bf16 v[120:123], v[150:153], v[134:137], v[120:123]
	v_mfma_f32_16x16x32_bf16 v[116:119], v[150:153], v[138:141], v[116:119]
	v_mfma_f32_16x16x32_bf16 v[112:115], v[150:153], v[142:145], v[112:115]
	v_mfma_f32_16x16x32_bf16 v[108:111], v[154:157], v[130:133], v[108:111]
	v_mfma_f32_16x16x32_bf16 v[104:107], v[154:157], v[134:137], v[104:107]
	v_mfma_f32_16x16x32_bf16 v[100:103], v[154:157], v[138:141], v[100:103]
	v_mfma_f32_16x16x32_bf16 v[96:99], v[154:157], v[142:145], v[96:99]
	v_mfma_f32_16x16x32_bf16 v[150:153], v[158:161], v[130:133], v[92:95]
	v_mfma_f32_16x16x32_bf16 v[84:87], v[158:161], v[134:137], v[84:87]
	v_mfma_f32_16x16x32_bf16 v[154:157], v[158:161], v[138:141], v[80:83]
	v_mfma_f32_16x16x32_bf16 v[76:79], v[158:161], v[142:145], v[76:79]
	v_mfma_f32_16x16x32_bf16 v[72:75], v[162:165], v[130:133], v[72:75]
	v_mfma_f32_16x16x32_bf16 v[68:71], v[162:165], v[134:137], v[68:71]
	v_mfma_f32_16x16x32_bf16 v[64:67], v[162:165], v[138:141], v[64:67]
	v_mfma_f32_16x16x32_bf16 v[158:161], v[162:165], v[142:145], v[60:63]
	s_nop 2
	v_add_u32_e32 v60, s9, v148
	v_add_u32_e32 v61, v60, v147
	v_add_u32_e32 v92, v60, v146
	ds_read_b128 v[162:165], v61 offset:32768
	ds_read_b128 v[186:189], v61 offset:34816
	ds_read_b128 v[190:193], v61 offset:36864
	ds_read_b128 v[194:197], v61 offset:38912
	ds_read_b128 v[60:63], v92
	ds_read_b128 v[80:83], v92 offset:2048
	ds_read_b128 v[146:149], v92 offset:4096
	ds_read_b128 v[198:201], v92 offset:6144
	v_mfma_f32_16x16x32_bf16 v[202:205], v[166:169], v[130:133], v[56:59]
	v_mfma_f32_16x16x32_bf16 v[206:209], v[166:169], v[134:137], v[52:55]
	v_mfma_f32_16x16x32_bf16 v[210:213], v[166:169], v[138:141], v[48:51]
	v_mfma_f32_16x16x32_bf16 v[44:47], v[166:169], v[142:145], v[44:47]
	v_mfma_f32_16x16x32_bf16 v[166:169], v[170:173], v[130:133], v[40:43]
	v_mfma_f32_16x16x32_bf16 v[36:39], v[170:173], v[134:137], v[36:39]
	v_mfma_f32_16x16x32_bf16 v[32:35], v[170:173], v[138:141], v[32:35]
	v_mfma_f32_16x16x32_bf16 v[214:217], v[174:177], v[130:133], v[24:27]
	v_mfma_f32_16x16x32_bf16 v[130:133], v[180:183], v[130:133], v[8:11]
	v_mfma_f32_16x16x32_bf16 v[4:7], v[180:183], v[134:137], v[4:7]
	v_mfma_f32_16x16x32_bf16 v[170:173], v[170:173], v[142:145], v[28:31]
	v_mfma_f32_16x16x32_bf16 v[218:221], v[174:177], v[134:137], v[20:23]
	v_mfma_f32_16x16x32_bf16 v[222:225], v[174:177], v[138:141], v[16:19]
	v_mfma_f32_16x16x32_bf16 v[174:177], v[174:177], v[142:145], v[12:15]
	v_mfma_f32_16x16x32_bf16 v[134:137], v[180:183], v[138:141], v[0:3]
	v_mfma_f32_16x16x32_bf16 v[138:141], v[180:183], v[142:145], v[88:91]
	s_nop 1
	ds_read_b128 v[0:3], v92 offset:8192
	ds_read_b128 v[12:15], v92 offset:10240
	ds_read_b128 v[142:145], v92 offset:12288
	ds_read_b128 v[180:183], v92 offset:14336
	s_waitcnt lgkmcnt(0)
	v_mfma_f32_16x16x32_bf16 v[124:127], v[60:63], v[162:165], v[124:127]
	v_mfma_f32_16x16x32_bf16 v[88:91], v[60:63], v[186:189], v[120:123]
	v_mfma_f32_16x16x32_bf16 v[56:59], v[60:63], v[190:193], v[116:119]
	v_mfma_f32_16x16x32_bf16 v[24:27], v[60:63], v[194:197], v[112:115]
	v_mfma_f32_16x16x32_bf16 v[120:123], v[80:83], v[162:165], v[108:111]
	v_mfma_f32_16x16x32_bf16 v[92:95], v[80:83], v[186:189], v[104:107]
	v_mfma_f32_16x16x32_bf16 v[60:63], v[80:83], v[190:193], v[100:103]
	v_mfma_f32_16x16x32_bf16 v[28:31], v[80:83], v[194:197], v[96:99]
	v_mfma_f32_16x16x32_bf16 v[112:115], v[146:149], v[162:165], v[150:153]
	v_mfma_f32_16x16x32_bf16 v[80:83], v[146:149], v[186:189], v[84:87]
	v_mfma_f32_16x16x32_bf16 v[48:51], v[146:149], v[190:193], v[154:157]
	v_mfma_f32_16x16x32_bf16 v[16:19], v[146:149], v[194:197], v[76:79]
	v_mfma_f32_16x16x32_bf16 v[116:119], v[198:201], v[162:165], v[72:75]
	v_mfma_f32_16x16x32_bf16 v[84:87], v[198:201], v[186:189], v[68:71]
	v_mfma_f32_16x16x32_bf16 v[52:55], v[198:201], v[190:193], v[64:67]
	v_mfma_f32_16x16x32_bf16 v[20:23], v[198:201], v[194:197], v[158:161]
	s_waitcnt vmcnt(0)
	v_mov_b32_e32 v154, v184
	s_waitcnt lgkmcnt(0)
	s_barrier
	v_mfma_f32_16x16x32_bf16 v[68:71], v[180:183], v[186:189], v[4:7]
	v_bfe_u32 v128, v154, 6, 2
	v_and_b32_e32 v152, 15, v154
	v_ashrrev_i32_e32 v153, 8, v154
	v_lshrrev_b32_e32 v4, 2, v154
	v_and_b32_e32 v155, 12, v4
	v_lshlrev_b32_e32 v4, 6, v128
	v_mfma_f32_16x16x32_bf16 v[104:107], v[0:3], v[162:165], v[202:205]
	s_cmpk_lt_u32 s31, 0x1101
	s_mov_b64 s[2:3], -1
	v_mfma_f32_16x16x32_bf16 v[72:75], v[0:3], v[186:189], v[206:209]
	v_mfma_f32_16x16x32_bf16 v[40:43], v[0:3], v[190:193], v[210:213]
	v_mfma_f32_16x16x32_bf16 v[8:11], v[0:3], v[194:197], v[44:47]
	v_mfma_f32_16x16x32_bf16 v[108:111], v[12:15], v[162:165], v[166:169]
	v_mfma_f32_16x16x32_bf16 v[76:79], v[12:15], v[186:189], v[36:39]
	v_mfma_f32_16x16x32_bf16 v[44:47], v[12:15], v[190:193], v[32:35]
	v_mfma_f32_16x16x32_bf16 v[12:15], v[12:15], v[194:197], v[170:173]
	v_mfma_f32_16x16x32_bf16 v[96:99], v[142:145], v[162:165], v[214:217]
	v_mfma_f32_16x16x32_bf16 v[64:67], v[142:145], v[186:189], v[218:221]
	v_mfma_f32_16x16x32_bf16 v[32:35], v[142:145], v[190:193], v[222:225]
	v_mfma_f32_16x16x32_bf16 v[0:3], v[142:145], v[194:197], v[174:177]
	v_mfma_f32_16x16x32_bf16 v[100:103], v[180:183], v[162:165], v[130:133]
	v_mfma_f32_16x16x32_bf16 v[36:39], v[180:183], v[190:193], v[134:137]
	s_nop 1
	v_or3_b32 v130, v4, v152, s4
	v_cvt_pk_bf16_f32 v132, v124, v125
	v_cvt_pk_bf16_f32 v133, v126, v127
	v_mfma_f32_16x16x32_bf16 v[4:7], v[180:183], v[194:197], v[138:141]
	s_cbranch_scc1 .LBB0_863
	v_lshl_or_b32 v136, v153, 7, v155
	v_add_u32_e32 v134, s31, v136
	v_cmp_lt_i32_e64 s[16:17], s52, v134
	s_and_saveexec_b64 s[2:3], s[16:17]
	s_xor_b64 s[4:5], exec, s[2:3]
	s_cbranch_execz .LBB0_148
	v_cmp_lt_u32_e32 vcc, s53, v134
	s_and_saveexec_b64 s[2:3], vcc
	s_xor_b64 s[6:7], exec, s[2:3]
	s_cbranch_execz .LBB0_145
	v_cmp_lt_u32_e32 vcc, s54, v134
	s_and_saveexec_b64 s[2:3], vcc
	s_xor_b64 s[8:9], exec, s[2:3]
	s_cbranch_execz .LBB0_142
	v_cmp_lt_u32_e32 vcc, s55, v134
	s_and_saveexec_b64 s[2:3], vcc
	s_xor_b64 s[10:11], exec, s[2:3]
	s_cbranch_execz .LBB0_139
	v_cmp_lt_u32_e32 vcc, s56, v134
	s_and_saveexec_b64 s[2:3], vcc
	s_xor_b64 s[2:3], exec, s[2:3]
	s_cbranch_execz .LBB0_134
	v_cmp_gt_u32_e32 vcc, s57, v134
	s_and_saveexec_b64 s[12:13], vcc
	s_cbranch_execz .LBB0_133
	v_ashrrev_i32_e32 v131, 31, v130
	v_lshlrev_b64 v[138:139], 7, v[130:131]
	v_lshl_add_u64 v[138:139], s[20:21], 0, v[138:139]
	v_mov_b32_e32 v135, v129
	v_lshl_add_u64 v[138:139], v[134:135], 2, v[138:139]
	v_add_co_u32_e32 v138, vcc, 0xefb000, v138
	s_nop 1
	v_addc_co_u32_e32 v139, vcc, 0, v139, vcc
	global_store_dwordx4 v[138:139], v[124:127], off offset:2048
